# v41 with MFMA chains (same accumulator back to back) in snake order, alternate chains accumulate k=1 before k=0
# speedup vs baseline: 1.0358x; 1.0358x over previous
.LBB0_159:
	s_add_u32 s0, s22, 0xfff80080
	s_addc_u32 s1, s23, -1
	s_add_i32 s51, 0, 0x10000
	s_cmp_eq_u32 s50, 28
	s_cselect_b32 s27, s15, s1
	s_cselect_b32 s26, s46, s0
	v_add_u32_e32 v140, s51, v143
	s_cselect_b32 s25, s13, s49
	s_cselect_b32 s24, s47, s48
	s_add_i32 s0, 0, 0x14000
	ds_read_b128 v[146:149], v140
	ds_read_b128 v[150:153], v140 offset:1024
	ds_read_b128 v[154:157], v140 offset:2048
	ds_read_b128 v[158:161], v140 offset:3072
	v_add_u32_e32 v140, s0, v143
	ds_read_b128 v[162:165], v140
	ds_read_b128 v[166:169], v140 offset:1024
	ds_read_b128 v[170:173], v140 offset:2048
	ds_read_b128 v[174:177], v140 offset:3072
	v_lshl_add_u64 v[140:141], s[22:23], 0, v[136:137]
	s_add_i32 m0, s35, 0xc000
	ds_read_b128 v[178:181], v144
	ds_read_b128 v[182:185], v144 offset:1024
	ds_read_b128 v[192:195], v144 offset:2048
	ds_read_b128 v[196:199], v144 offset:3072
	ds_read_b128 v[200:203], v144 offset:4096
	ds_read_b128 v[204:207], v144 offset:5120
	ds_read_b128 v[208:211], v144 offset:6144
	ds_read_b128 v[212:215], v144 offset:7168
	global_load_lds_dwordx4 v[140:141], off
	v_lshl_add_u64 v[140:141], s[22:23], 0, v[138:139]
	s_add_i32 m0, s35, 0xe000
	s_nop 0
	global_load_lds_dwordx4 v[140:141], off
	s_waitcnt vmcnt(8)
	s_waitcnt lgkmcnt(0)
	s_setprio 1
	s_barrier

	v_mfma_f32_16x16x32_bf16 v[126:129], v[146:149], v[178:181], v[126:129]
	v_mfma_f32_16x16x32_bf16 v[126:129], v[150:153], v[182:185], v[126:129]
	v_mfma_f32_16x16x32_bf16 v[118:121], v[158:161], v[182:185], v[118:121]
	v_mfma_f32_16x16x32_bf16 v[118:121], v[154:157], v[178:181], v[118:121]
	v_mfma_f32_16x16x32_bf16 v[102:105], v[154:157], v[192:195], v[102:105]
	v_mfma_f32_16x16x32_bf16 v[102:105], v[158:161], v[196:199], v[102:105]
	v_mfma_f32_16x16x32_bf16 v[110:113], v[150:153], v[196:199], v[110:113]
	v_mfma_f32_16x16x32_bf16 v[110:113], v[146:149], v[192:195], v[110:113]
	v_mfma_f32_16x16x32_bf16 v[94:97], v[146:149], v[200:203], v[94:97]
	v_mfma_f32_16x16x32_bf16 v[94:97], v[150:153], v[204:207], v[94:97]
	v_mfma_f32_16x16x32_bf16 v[86:89], v[158:161], v[204:207], v[86:89]
	v_mfma_f32_16x16x32_bf16 v[86:89], v[154:157], v[200:203], v[86:89]
	v_mfma_f32_16x16x32_bf16 v[70:73], v[154:157], v[208:211], v[70:73]
	v_mfma_f32_16x16x32_bf16 v[70:73], v[158:161], v[212:215], v[70:73]
	v_mfma_f32_16x16x32_bf16 v[78:81], v[150:153], v[212:215], v[78:81]
	v_mfma_f32_16x16x32_bf16 v[78:81], v[146:149], v[208:211], v[78:81]


	v_mfma_f32_16x16x32_bf16 v[122:125], v[162:165], v[178:181], v[122:125]
	v_mfma_f32_16x16x32_bf16 v[122:125], v[166:169], v[182:185], v[122:125]
	v_mfma_f32_16x16x32_bf16 v[114:117], v[174:177], v[182:185], v[114:117]
	v_mfma_f32_16x16x32_bf16 v[114:117], v[170:173], v[178:181], v[114:117]
	v_mfma_f32_16x16x32_bf16 v[98:101], v[170:173], v[192:195], v[98:101]
	v_mfma_f32_16x16x32_bf16 v[98:101], v[174:177], v[196:199], v[98:101]
	v_mfma_f32_16x16x32_bf16 v[106:109], v[166:169], v[196:199], v[106:109]
	v_mfma_f32_16x16x32_bf16 v[106:109], v[162:165], v[192:195], v[106:109]
	v_mfma_f32_16x16x32_bf16 v[90:93], v[162:165], v[200:203], v[90:93]
	v_mfma_f32_16x16x32_bf16 v[90:93], v[166:169], v[204:207], v[90:93]
	v_mfma_f32_16x16x32_bf16 v[82:85], v[174:177], v[204:207], v[82:85]
	v_mfma_f32_16x16x32_bf16 v[82:85], v[170:173], v[200:203], v[82:85]
	v_mfma_f32_16x16x32_bf16 v[66:69], v[170:173], v[208:211], v[66:69]
	v_mfma_f32_16x16x32_bf16 v[66:69], v[174:177], v[212:215], v[66:69]
	v_mfma_f32_16x16x32_bf16 v[74:77], v[166:169], v[212:215], v[74:77]
	v_mfma_f32_16x16x32_bf16 v[74:77], v[162:165], v[208:211], v[74:77]
	s_barrier
	s_setprio 0
	s_add_i32 s1, s51, s31
	v_lshl_add_u64 v[140:141], s[24:25], 0, v[186:187]
	s_mov_b32 m0, s1
	ds_read_b128 v[178:181], v144 offset:16384
	ds_read_b128 v[182:185], v144 offset:17408
	ds_read_b128 v[192:195], v144 offset:18432
	ds_read_b128 v[196:199], v144 offset:19456
	ds_read_b128 v[200:203], v144 offset:20480
	ds_read_b128 v[204:207], v144 offset:21504
	ds_read_b128 v[208:211], v144 offset:22528
	ds_read_b128 v[212:215], v144 offset:23552
	global_load_lds_dwordx4 v[140:141], off
	s_add_i32 m0, s1, 0x2000
	s_add_u32 s52, s24, 0x80000
	v_lshl_add_u64 v[216:217], s[24:25], 0, v[130:131]
	s_addc_u32 s53, s25, 0
	s_add_i32 s0, s0, s31
	global_load_lds_dwordx4 v[216:217], off
	v_lshl_add_u64 v[218:219], s[52:53], 0, v[186:187]
	s_mov_b32 m0, s0
	v_lshl_add_u64 v[220:221], s[26:27], 0, v[132:133]
	global_load_lds_dwordx4 v[218:219], off
	v_lshl_add_u64 v[218:219], s[52:53], 0, v[130:131]
	s_add_i32 m0, s0, 0x2000
	s_nop 0
	global_load_lds_dwordx4 v[218:219], off
	v_lshl_add_u64 v[218:219], s[26:27], 0, v[134:135]
	s_mov_b32 m0, s35
	s_nop 0
	global_load_lds_dwordx4 v[218:219], off
	s_mov_b32 m0, s36
	s_nop 0
	global_load_lds_dwordx4 v[220:221], off
	s_waitcnt vmcnt(8)
	s_waitcnt lgkmcnt(0)
	s_setprio 1
	s_barrier

	v_mfma_f32_16x16x32_bf16 v[62:65], v[146:149], v[178:181], v[62:65]
	v_mfma_f32_16x16x32_bf16 v[62:65], v[150:153], v[182:185], v[62:65]
	v_mfma_f32_16x16x32_bf16 v[54:57], v[158:161], v[182:185], v[54:57]
	v_mfma_f32_16x16x32_bf16 v[54:57], v[154:157], v[178:181], v[54:57]
	v_mfma_f32_16x16x32_bf16 v[38:41], v[154:157], v[192:195], v[38:41]
	v_mfma_f32_16x16x32_bf16 v[38:41], v[158:161], v[196:199], v[38:41]
	v_mfma_f32_16x16x32_bf16 v[46:49], v[150:153], v[196:199], v[46:49]
	v_mfma_f32_16x16x32_bf16 v[46:49], v[146:149], v[192:195], v[46:49]
	v_mfma_f32_16x16x32_bf16 v[30:33], v[146:149], v[200:203], v[30:33]
	v_mfma_f32_16x16x32_bf16 v[30:33], v[150:153], v[204:207], v[30:33]
	v_mfma_f32_16x16x32_bf16 v[22:25], v[158:161], v[204:207], v[22:25]
	v_mfma_f32_16x16x32_bf16 v[22:25], v[154:157], v[200:203], v[22:25]
	v_mfma_f32_16x16x32_bf16 v[6:9], v[154:157], v[208:211], v[6:9]
	v_mfma_f32_16x16x32_bf16 v[6:9], v[158:161], v[212:215], v[6:9]
	v_mfma_f32_16x16x32_bf16 v[14:17], v[150:153], v[212:215], v[14:17]
	v_mfma_f32_16x16x32_bf16 v[14:17], v[146:149], v[208:211], v[14:17]


	v_mfma_f32_16x16x32_bf16 v[58:61], v[162:165], v[178:181], v[58:61]
	v_mfma_f32_16x16x32_bf16 v[58:61], v[166:169], v[182:185], v[58:61]
	v_mfma_f32_16x16x32_bf16 v[50:53], v[174:177], v[182:185], v[50:53]
	v_mfma_f32_16x16x32_bf16 v[50:53], v[170:173], v[178:181], v[50:53]
	v_mfma_f32_16x16x32_bf16 v[34:37], v[170:173], v[192:195], v[34:37]
	v_mfma_f32_16x16x32_bf16 v[34:37], v[174:177], v[196:199], v[34:37]
	v_mfma_f32_16x16x32_bf16 v[42:45], v[166:169], v[196:199], v[42:45]
	v_mfma_f32_16x16x32_bf16 v[42:45], v[162:165], v[192:195], v[42:45]
	v_mfma_f32_16x16x32_bf16 v[26:29], v[162:165], v[200:203], v[26:29]
	v_mfma_f32_16x16x32_bf16 v[26:29], v[166:169], v[204:207], v[26:29]
	v_mfma_f32_16x16x32_bf16 v[18:21], v[174:177], v[204:207], v[18:21]
	v_mfma_f32_16x16x32_bf16 v[18:21], v[170:173], v[200:203], v[18:21]
	v_mfma_f32_16x16x32_bf16 v[2:5], v[170:173], v[208:211], v[2:5]
	v_mfma_f32_16x16x32_bf16 v[2:5], v[174:177], v[212:215], v[2:5]
	v_mfma_f32_16x16x32_bf16 v[10:13], v[166:169], v[212:215], v[10:13]
	v_mfma_f32_16x16x32_bf16 v[10:13], v[162:165], v[208:211], v[10:13]
	s_barrier
	s_setprio 0
	s_add_i32 s0, 0, 0x18000
	v_add_u32_e32 v145, s0, v143
	s_add_i32 s1, 0, 0x1c000
	ds_read_b128 v[146:149], v145
	ds_read_b128 v[150:153], v145 offset:1024
	ds_read_b128 v[154:157], v145 offset:2048
	ds_read_b128 v[158:161], v145 offset:3072
	v_add_u32_e32 v145, s1, v143
	ds_read_b128 v[162:165], v145
	ds_read_b128 v[166:169], v145 offset:1024
	ds_read_b128 v[170:173], v145 offset:2048
	ds_read_b128 v[174:177], v145 offset:3072
	s_add_u32 s26, s26, 0x80000
	s_addc_u32 s27, s27, 0
	s_mov_b32 m0, s37
	v_lshl_add_u64 v[222:223], s[26:27], 0, v[134:135]
	ds_read_b128 v[178:181], v144 offset:32768
	ds_read_b128 v[182:185], v144 offset:33792
	ds_read_b128 v[192:195], v144 offset:34816
	ds_read_b128 v[196:199], v144 offset:35840
	ds_read_b128 v[200:203], v144 offset:36864
	ds_read_b128 v[204:207], v144 offset:37888
	ds_read_b128 v[208:211], v144 offset:38912
	ds_read_b128 v[212:215], v144 offset:39936
	global_load_lds_dwordx4 v[222:223], off
	v_lshl_add_u64 v[222:223], s[26:27], 0, v[132:133]
	s_mov_b32 m0, s38
	s_nop 0
	global_load_lds_dwordx4 v[222:223], off
	s_waitcnt vmcnt(8)
	s_waitcnt lgkmcnt(0)
	s_setprio 1
	s_barrier

	v_mfma_f32_16x16x32_bf16 v[126:129], v[146:149], v[178:181], v[126:129]
	v_mfma_f32_16x16x32_bf16 v[126:129], v[150:153], v[182:185], v[126:129]
	v_mfma_f32_16x16x32_bf16 v[118:121], v[158:161], v[182:185], v[118:121]
	v_mfma_f32_16x16x32_bf16 v[118:121], v[154:157], v[178:181], v[118:121]
	v_mfma_f32_16x16x32_bf16 v[102:105], v[154:157], v[192:195], v[102:105]
	v_mfma_f32_16x16x32_bf16 v[102:105], v[158:161], v[196:199], v[102:105]
	v_mfma_f32_16x16x32_bf16 v[110:113], v[150:153], v[196:199], v[110:113]
	v_mfma_f32_16x16x32_bf16 v[110:113], v[146:149], v[192:195], v[110:113]
	v_mfma_f32_16x16x32_bf16 v[94:97], v[146:149], v[200:203], v[94:97]
	v_mfma_f32_16x16x32_bf16 v[94:97], v[150:153], v[204:207], v[94:97]
	v_mfma_f32_16x16x32_bf16 v[86:89], v[158:161], v[204:207], v[86:89]
	v_mfma_f32_16x16x32_bf16 v[86:89], v[154:157], v[200:203], v[86:89]
	v_mfma_f32_16x16x32_bf16 v[70:73], v[154:157], v[208:211], v[70:73]
	v_mfma_f32_16x16x32_bf16 v[70:73], v[158:161], v[212:215], v[70:73]
	v_mfma_f32_16x16x32_bf16 v[78:81], v[150:153], v[212:215], v[78:81]
	v_mfma_f32_16x16x32_bf16 v[78:81], v[146:149], v[208:211], v[78:81]


	v_mfma_f32_16x16x32_bf16 v[122:125], v[162:165], v[178:181], v[122:125]
	v_mfma_f32_16x16x32_bf16 v[122:125], v[166:169], v[182:185], v[122:125]
	v_mfma_f32_16x16x32_bf16 v[114:117], v[174:177], v[182:185], v[114:117]
	v_mfma_f32_16x16x32_bf16 v[114:117], v[170:173], v[178:181], v[114:117]
	v_mfma_f32_16x16x32_bf16 v[98:101], v[170:173], v[192:195], v[98:101]
	v_mfma_f32_16x16x32_bf16 v[98:101], v[174:177], v[196:199], v[98:101]
	v_mfma_f32_16x16x32_bf16 v[106:109], v[166:169], v[196:199], v[106:109]
	v_mfma_f32_16x16x32_bf16 v[106:109], v[162:165], v[192:195], v[106:109]
	v_mfma_f32_16x16x32_bf16 v[90:93], v[162:165], v[200:203], v[90:93]
	v_mfma_f32_16x16x32_bf16 v[90:93], v[166:169], v[204:207], v[90:93]
	v_mfma_f32_16x16x32_bf16 v[82:85], v[174:177], v[204:207], v[82:85]
	v_mfma_f32_16x16x32_bf16 v[82:85], v[170:173], v[200:203], v[82:85]
	v_mfma_f32_16x16x32_bf16 v[66:69], v[170:173], v[208:211], v[66:69]
	v_mfma_f32_16x16x32_bf16 v[66:69], v[174:177], v[212:215], v[66:69]
	v_mfma_f32_16x16x32_bf16 v[74:77], v[166:169], v[212:215], v[74:77]
	v_mfma_f32_16x16x32_bf16 v[74:77], v[162:165], v[208:211], v[74:77]
	s_barrier
	s_setprio 0
	s_add_i32 s0, s0, s31
	v_lshl_add_u64 v[140:141], v[140:141], 0, s[84:85]
	s_mov_b32 m0, s0
	ds_read_b128 v[178:181], v144 offset:49152
	ds_read_b128 v[182:185], v144 offset:50176
	ds_read_b128 v[192:195], v144 offset:51200
	ds_read_b128 v[196:199], v144 offset:52224
	ds_read_b128 v[200:203], v144 offset:53248
	ds_read_b128 v[204:207], v144 offset:54272
	ds_read_b128 v[208:211], v144 offset:55296
	ds_read_b128 v[212:215], v144 offset:56320
	global_load_lds_dwordx4 v[140:141], off
	s_add_i32 m0, s0, 0x2000
	s_add_u32 s24, s24, 0x80080
	v_lshl_add_u64 v[140:141], v[216:217], 0, s[84:85]
	s_addc_u32 s25, s25, 0
	s_add_i32 s0, s1, s31
	global_load_lds_dwordx4 v[140:141], off
	v_lshl_add_u64 v[140:141], s[24:25], 0, v[186:187]
	s_mov_b32 m0, s0
	s_nop 0
	global_load_lds_dwordx4 v[140:141], off
	v_lshl_add_u64 v[140:141], s[24:25], 0, v[130:131]
	s_add_i32 m0, s0, 0x2000
	s_nop 0
	global_load_lds_dwordx4 v[140:141], off
	v_lshl_add_u64 v[140:141], v[218:219], 0, s[84:85]
	s_mov_b32 m0, s39
	s_nop 0
	global_load_lds_dwordx4 v[140:141], off
	v_lshl_add_u64 v[140:141], v[220:221], 0, s[84:85]
	s_mov_b32 m0, s40
	s_nop 0
	global_load_lds_dwordx4 v[140:141], off
	s_waitcnt vmcnt(8)
	s_waitcnt lgkmcnt(0)
	s_setprio 1
	s_barrier

	v_mfma_f32_16x16x32_bf16 v[62:65], v[146:149], v[178:181], v[62:65]
	v_mfma_f32_16x16x32_bf16 v[62:65], v[150:153], v[182:185], v[62:65]
	v_mfma_f32_16x16x32_bf16 v[54:57], v[158:161], v[182:185], v[54:57]
	v_mfma_f32_16x16x32_bf16 v[54:57], v[154:157], v[178:181], v[54:57]
	v_mfma_f32_16x16x32_bf16 v[38:41], v[154:157], v[192:195], v[38:41]
	v_mfma_f32_16x16x32_bf16 v[38:41], v[158:161], v[196:199], v[38:41]
	v_mfma_f32_16x16x32_bf16 v[46:49], v[150:153], v[196:199], v[46:49]
	v_mfma_f32_16x16x32_bf16 v[46:49], v[146:149], v[192:195], v[46:49]
	v_mfma_f32_16x16x32_bf16 v[30:33], v[146:149], v[200:203], v[30:33]
	v_mfma_f32_16x16x32_bf16 v[30:33], v[150:153], v[204:207], v[30:33]
	v_mfma_f32_16x16x32_bf16 v[22:25], v[158:161], v[204:207], v[22:25]
	v_mfma_f32_16x16x32_bf16 v[22:25], v[154:157], v[200:203], v[22:25]
	v_mfma_f32_16x16x32_bf16 v[6:9], v[154:157], v[208:211], v[6:9]
	v_mfma_f32_16x16x32_bf16 v[6:9], v[158:161], v[212:215], v[6:9]
	v_mfma_f32_16x16x32_bf16 v[14:17], v[150:153], v[212:215], v[14:17]
	v_mfma_f32_16x16x32_bf16 v[14:17], v[146:149], v[208:211], v[14:17]


	v_mfma_f32_16x16x32_bf16 v[58:61], v[162:165], v[178:181], v[58:61]
	v_mfma_f32_16x16x32_bf16 v[58:61], v[166:169], v[182:185], v[58:61]
	v_mfma_f32_16x16x32_bf16 v[50:53], v[174:177], v[182:185], v[50:53]
	v_mfma_f32_16x16x32_bf16 v[50:53], v[170:173], v[178:181], v[50:53]
	v_mfma_f32_16x16x32_bf16 v[34:37], v[170:173], v[192:195], v[34:37]
	v_mfma_f32_16x16x32_bf16 v[34:37], v[174:177], v[196:199], v[34:37]
	v_mfma_f32_16x16x32_bf16 v[42:45], v[166:169], v[196:199], v[42:45]
	v_mfma_f32_16x16x32_bf16 v[42:45], v[162:165], v[192:195], v[42:45]
	v_mfma_f32_16x16x32_bf16 v[26:29], v[162:165], v[200:203], v[26:29]
	v_mfma_f32_16x16x32_bf16 v[26:29], v[166:169], v[204:207], v[26:29]
	v_mfma_f32_16x16x32_bf16 v[18:21], v[174:177], v[204:207], v[18:21]
	v_mfma_f32_16x16x32_bf16 v[18:21], v[170:173], v[200:203], v[18:21]
	v_mfma_f32_16x16x32_bf16 v[2:5], v[170:173], v[208:211], v[2:5]
	v_mfma_f32_16x16x32_bf16 v[2:5], v[174:177], v[212:215], v[2:5]
	v_mfma_f32_16x16x32_bf16 v[10:13], v[166:169], v[212:215], v[10:13]
	v_mfma_f32_16x16x32_bf16 v[10:13], v[162:165], v[208:211], v[10:13]
	s_barrier
	s_setprio 0
	s_add_i32 s50, s50, 2
	s_add_u32 s22, s22, 0x100
	s_addc_u32 s23, s23, 0
	s_add_u32 s48, s48, 0x100
	s_addc_u32 s49, s49, 0
	s_cmp_gt_u32 s50, 29
	s_cbranch_scc0 .LBB0_159
	s_and_b64 vcc, exec, s[10:11]
	s_cbranch_vccz .LBB0_162
	s_barrier

.LBB0_243:
	s_add_u32 s22, s20, 0x100
	s_addc_u32 s23, s21, 0
	s_add_i32 s0, 0, 0x10000
	s_cmpk_eq_i32 s51, 0x54
	s_cselect_b32 s27, s7, s23
	s_cselect_b32 s26, s6, s22
	s_cselect_b32 s25, s19, s50
	s_cselect_b32 s24, s18, s49
	s_add_i32 s1, 0, 0x14000
	v_add_u32_e32 v126, s0, v237
	v_add_u32_e32 v158, s1, v237
	ds_read_b128 v[90:93], v126
	ds_read_b128 v[102:105], v126 offset:1024
	ds_read_b128 v[114:117], v126 offset:2048
	ds_read_b128 v[126:129], v126 offset:3072
	ds_read_b128 v[138:141], v158
	ds_read_b128 v[142:145], v158 offset:1024
	ds_read_b128 v[154:157], v158 offset:2048
	ds_read_b128 v[158:161], v158 offset:3072
	v_lshl_add_u64 v[210:211], s[20:21], 0, v[198:199]
	s_add_i32 m0, s34, 0xc000
	ds_read_b128 v[162:165], v238
	ds_read_b128 v[166:169], v238 offset:1024
	ds_read_b128 v[170:173], v238 offset:2048
	ds_read_b128 v[174:177], v238 offset:3072
	ds_read_b128 v[178:181], v238 offset:4096
	ds_read_b128 v[182:185], v238 offset:5120
	ds_read_b128 v[202:205], v238 offset:6144
	ds_read_b128 v[206:209], v238 offset:7168
	global_load_lds_dwordx4 v[210:211], off
	v_lshl_add_u64 v[210:211], s[20:21], 0, v[200:201]
	s_add_i32 m0, s34, 0xe000
	s_nop 0
	global_load_lds_dwordx4 v[210:211], off
	s_waitcnt vmcnt(8)
	s_waitcnt lgkmcnt(0)
	s_setprio 1
	s_barrier

	v_mfma_f32_16x16x32_bf16 v[150:153], v[90:93], v[162:165], v[150:153]
	v_mfma_f32_16x16x32_bf16 v[150:153], v[102:105], v[166:169], v[150:153]
	v_mfma_f32_16x16x32_bf16 v[146:149], v[126:129], v[166:169], v[146:149]
	v_mfma_f32_16x16x32_bf16 v[146:149], v[114:117], v[162:165], v[146:149]
	v_mfma_f32_16x16x32_bf16 v[118:121], v[114:117], v[170:173], v[118:121]
	v_mfma_f32_16x16x32_bf16 v[118:121], v[126:129], v[174:177], v[118:121]
	v_mfma_f32_16x16x32_bf16 v[122:125], v[102:105], v[174:177], v[122:125]
	v_mfma_f32_16x16x32_bf16 v[122:125], v[90:93], v[170:173], v[122:125]
	v_mfma_f32_16x16x32_bf16 v[98:101], v[90:93], v[178:181], v[98:101]
	v_mfma_f32_16x16x32_bf16 v[98:101], v[102:105], v[182:185], v[98:101]
	v_mfma_f32_16x16x32_bf16 v[94:97], v[126:129], v[182:185], v[94:97]
	v_mfma_f32_16x16x32_bf16 v[94:97], v[114:117], v[178:181], v[94:97]
	v_mfma_f32_16x16x32_bf16 v[74:77], v[114:117], v[202:205], v[74:77]
	v_mfma_f32_16x16x32_bf16 v[74:77], v[126:129], v[206:209], v[74:77]
	v_mfma_f32_16x16x32_bf16 v[78:81], v[102:105], v[206:209], v[78:81]
	v_mfma_f32_16x16x32_bf16 v[78:81], v[90:93], v[202:205], v[78:81]


	v_mfma_f32_16x16x32_bf16 v[134:137], v[138:141], v[162:165], v[134:137]
	v_mfma_f32_16x16x32_bf16 v[134:137], v[142:145], v[166:169], v[134:137]
	v_mfma_f32_16x16x32_bf16 v[130:133], v[158:161], v[166:169], v[130:133]
	v_mfma_f32_16x16x32_bf16 v[130:133], v[154:157], v[162:165], v[130:133]
	v_mfma_f32_16x16x32_bf16 v[106:109], v[154:157], v[170:173], v[106:109]
	v_mfma_f32_16x16x32_bf16 v[106:109], v[158:161], v[174:177], v[106:109]
	v_mfma_f32_16x16x32_bf16 v[110:113], v[142:145], v[174:177], v[110:113]
	v_mfma_f32_16x16x32_bf16 v[110:113], v[138:141], v[170:173], v[110:113]
	v_mfma_f32_16x16x32_bf16 v[86:89], v[138:141], v[178:181], v[86:89]
	v_mfma_f32_16x16x32_bf16 v[86:89], v[142:145], v[182:185], v[86:89]
	v_mfma_f32_16x16x32_bf16 v[82:85], v[158:161], v[182:185], v[82:85]
	v_mfma_f32_16x16x32_bf16 v[82:85], v[154:157], v[178:181], v[82:85]
	v_mfma_f32_16x16x32_bf16 v[66:69], v[154:157], v[202:205], v[66:69]
	v_mfma_f32_16x16x32_bf16 v[66:69], v[158:161], v[206:209], v[66:69]
	v_mfma_f32_16x16x32_bf16 v[70:73], v[142:145], v[206:209], v[70:73]
	v_mfma_f32_16x16x32_bf16 v[70:73], v[138:141], v[202:205], v[70:73]
	s_barrier
	s_setprio 0
	s_add_i32 s0, s0, s31
	v_lshl_add_u64 v[210:211], s[24:25], 0, v[186:187]
	s_mov_b32 m0, s0
	ds_read_b128 v[162:165], v238 offset:16384
	ds_read_b128 v[166:169], v238 offset:17408
	ds_read_b128 v[170:173], v238 offset:18432
	ds_read_b128 v[174:177], v238 offset:19456
	ds_read_b128 v[178:181], v238 offset:20480
	ds_read_b128 v[182:185], v238 offset:21504
	ds_read_b128 v[202:205], v238 offset:22528
	ds_read_b128 v[206:209], v238 offset:23552
	global_load_lds_dwordx4 v[210:211], off
	s_add_i32 m0, s0, 0x2000
	s_add_u32 s20, s24, 0x160000
	v_lshl_add_u64 v[212:213], s[24:25], 0, v[196:197]
	s_addc_u32 s21, s25, 0
	s_add_i32 s0, s1, s31
	global_load_lds_dwordx4 v[212:213], off
	v_lshl_add_u64 v[214:215], s[20:21], 0, v[186:187]
	s_mov_b32 m0, s0
	v_lshl_add_u64 v[216:217], s[26:27], 0, v[194:195]
	global_load_lds_dwordx4 v[214:215], off
	v_lshl_add_u64 v[214:215], s[20:21], 0, v[196:197]
	s_add_i32 m0, s0, 0x2000
	s_nop 0
	global_load_lds_dwordx4 v[214:215], off
	v_lshl_add_u64 v[214:215], s[26:27], 0, v[192:193]
	s_mov_b32 m0, s34
	s_nop 0
	global_load_lds_dwordx4 v[214:215], off
	s_mov_b32 m0, s35
	s_nop 0
	global_load_lds_dwordx4 v[216:217], off
	s_waitcnt vmcnt(8)
	s_waitcnt lgkmcnt(0)
	s_setprio 1
	s_barrier

	v_mfma_f32_16x16x32_bf16 v[62:65], v[90:93], v[162:165], v[62:65]
	v_mfma_f32_16x16x32_bf16 v[62:65], v[102:105], v[166:169], v[62:65]
	v_mfma_f32_16x16x32_bf16 v[58:61], v[126:129], v[166:169], v[58:61]
	v_mfma_f32_16x16x32_bf16 v[58:61], v[114:117], v[162:165], v[58:61]
	v_mfma_f32_16x16x32_bf16 v[42:45], v[114:117], v[170:173], v[42:45]
	v_mfma_f32_16x16x32_bf16 v[42:45], v[126:129], v[174:177], v[42:45]
	v_mfma_f32_16x16x32_bf16 v[46:49], v[102:105], v[174:177], v[46:49]
	v_mfma_f32_16x16x32_bf16 v[46:49], v[90:93], v[170:173], v[46:49]
	v_mfma_f32_16x16x32_bf16 v[30:33], v[90:93], v[178:181], v[30:33]
	v_mfma_f32_16x16x32_bf16 v[30:33], v[102:105], v[182:185], v[30:33]
	v_mfma_f32_16x16x32_bf16 v[26:29], v[126:129], v[182:185], v[26:29]
	v_mfma_f32_16x16x32_bf16 v[26:29], v[114:117], v[178:181], v[26:29]
	v_mfma_f32_16x16x32_bf16 v[10:13], v[114:117], v[202:205], v[10:13]
	v_mfma_f32_16x16x32_bf16 v[10:13], v[126:129], v[206:209], v[10:13]
	v_mfma_f32_16x16x32_bf16 v[14:17], v[102:105], v[206:209], v[14:17]
	v_mfma_f32_16x16x32_bf16 v[14:17], v[90:93], v[202:205], v[14:17]


	v_mfma_f32_16x16x32_bf16 v[54:57], v[138:141], v[162:165], v[54:57]
	v_mfma_f32_16x16x32_bf16 v[54:57], v[142:145], v[166:169], v[54:57]
	v_mfma_f32_16x16x32_bf16 v[50:53], v[158:161], v[166:169], v[50:53]
	v_mfma_f32_16x16x32_bf16 v[50:53], v[154:157], v[162:165], v[50:53]
	v_mfma_f32_16x16x32_bf16 v[34:37], v[154:157], v[170:173], v[34:37]
	v_mfma_f32_16x16x32_bf16 v[34:37], v[158:161], v[174:177], v[34:37]
	v_mfma_f32_16x16x32_bf16 v[38:41], v[142:145], v[174:177], v[38:41]
	v_mfma_f32_16x16x32_bf16 v[38:41], v[138:141], v[170:173], v[38:41]
	v_mfma_f32_16x16x32_bf16 v[22:25], v[138:141], v[178:181], v[22:25]
	v_mfma_f32_16x16x32_bf16 v[22:25], v[142:145], v[182:185], v[22:25]
	v_mfma_f32_16x16x32_bf16 v[18:21], v[158:161], v[182:185], v[18:21]
	v_mfma_f32_16x16x32_bf16 v[18:21], v[154:157], v[178:181], v[18:21]
	v_mfma_f32_16x16x32_bf16 v[2:5], v[154:157], v[202:205], v[2:5]
	v_mfma_f32_16x16x32_bf16 v[2:5], v[158:161], v[206:209], v[2:5]
	v_mfma_f32_16x16x32_bf16 v[6:9], v[142:145], v[206:209], v[6:9]
	v_mfma_f32_16x16x32_bf16 v[6:9], v[138:141], v[202:205], v[6:9]
	s_barrier
	s_setprio 0
	s_add_i32 s0, 0, 0x18000
	s_add_i32 s1, 0, 0x1c000
	v_add_u32_e32 v126, s0, v237
	v_add_u32_e32 v158, s1, v237
	ds_read_b128 v[90:93], v126
	ds_read_b128 v[102:105], v126 offset:1024
	ds_read_b128 v[114:117], v126 offset:2048
	ds_read_b128 v[126:129], v126 offset:3072
	ds_read_b128 v[138:141], v158
	ds_read_b128 v[142:145], v158 offset:1024
	ds_read_b128 v[154:157], v158 offset:2048
	ds_read_b128 v[158:161], v158 offset:3072
	s_add_u32 s20, s26, 0x160000
	s_addc_u32 s21, s27, 0
	s_mov_b32 m0, s36
	v_lshl_add_u64 v[218:219], s[20:21], 0, v[192:193]
	ds_read_b128 v[162:165], v238 offset:32768
	ds_read_b128 v[166:169], v238 offset:33792
	ds_read_b128 v[170:173], v238 offset:34816
	ds_read_b128 v[174:177], v238 offset:35840
	ds_read_b128 v[178:181], v238 offset:36864
	ds_read_b128 v[182:185], v238 offset:37888
	ds_read_b128 v[202:205], v238 offset:38912
	ds_read_b128 v[206:209], v238 offset:39936
	global_load_lds_dwordx4 v[218:219], off
	v_lshl_add_u64 v[218:219], s[20:21], 0, v[194:195]
	s_mov_b32 m0, s37
	s_nop 0
	global_load_lds_dwordx4 v[218:219], off
	s_waitcnt vmcnt(8)
	s_waitcnt lgkmcnt(0)
	s_setprio 1
	s_barrier

	v_mfma_f32_16x16x32_bf16 v[150:153], v[90:93], v[162:165], v[150:153]
	v_mfma_f32_16x16x32_bf16 v[150:153], v[102:105], v[166:169], v[150:153]
	v_mfma_f32_16x16x32_bf16 v[146:149], v[126:129], v[166:169], v[146:149]
	v_mfma_f32_16x16x32_bf16 v[146:149], v[114:117], v[162:165], v[146:149]
	v_mfma_f32_16x16x32_bf16 v[118:121], v[114:117], v[170:173], v[118:121]
	v_mfma_f32_16x16x32_bf16 v[118:121], v[126:129], v[174:177], v[118:121]
	v_mfma_f32_16x16x32_bf16 v[122:125], v[102:105], v[174:177], v[122:125]
	v_mfma_f32_16x16x32_bf16 v[122:125], v[90:93], v[170:173], v[122:125]
	v_mfma_f32_16x16x32_bf16 v[98:101], v[90:93], v[178:181], v[98:101]
	v_mfma_f32_16x16x32_bf16 v[98:101], v[102:105], v[182:185], v[98:101]
	v_mfma_f32_16x16x32_bf16 v[94:97], v[126:129], v[182:185], v[94:97]
	v_mfma_f32_16x16x32_bf16 v[94:97], v[114:117], v[178:181], v[94:97]
	v_mfma_f32_16x16x32_bf16 v[74:77], v[114:117], v[202:205], v[74:77]
	v_mfma_f32_16x16x32_bf16 v[74:77], v[126:129], v[206:209], v[74:77]
	v_mfma_f32_16x16x32_bf16 v[78:81], v[102:105], v[206:209], v[78:81]
	v_mfma_f32_16x16x32_bf16 v[78:81], v[90:93], v[202:205], v[78:81]


	v_mfma_f32_16x16x32_bf16 v[134:137], v[138:141], v[162:165], v[134:137]
	v_mfma_f32_16x16x32_bf16 v[134:137], v[142:145], v[166:169], v[134:137]
	v_mfma_f32_16x16x32_bf16 v[130:133], v[158:161], v[166:169], v[130:133]
	v_mfma_f32_16x16x32_bf16 v[130:133], v[154:157], v[162:165], v[130:133]
	v_mfma_f32_16x16x32_bf16 v[106:109], v[154:157], v[170:173], v[106:109]
	v_mfma_f32_16x16x32_bf16 v[106:109], v[158:161], v[174:177], v[106:109]
	v_mfma_f32_16x16x32_bf16 v[110:113], v[142:145], v[174:177], v[110:113]
	v_mfma_f32_16x16x32_bf16 v[110:113], v[138:141], v[170:173], v[110:113]
	v_mfma_f32_16x16x32_bf16 v[86:89], v[138:141], v[178:181], v[86:89]
	v_mfma_f32_16x16x32_bf16 v[86:89], v[142:145], v[182:185], v[86:89]
	v_mfma_f32_16x16x32_bf16 v[82:85], v[158:161], v[182:185], v[82:85]
	v_mfma_f32_16x16x32_bf16 v[82:85], v[154:157], v[178:181], v[82:85]
	v_mfma_f32_16x16x32_bf16 v[66:69], v[154:157], v[202:205], v[66:69]
	v_mfma_f32_16x16x32_bf16 v[66:69], v[158:161], v[206:209], v[66:69]
	v_mfma_f32_16x16x32_bf16 v[70:73], v[142:145], v[206:209], v[70:73]
	v_mfma_f32_16x16x32_bf16 v[70:73], v[138:141], v[202:205], v[70:73]
	s_barrier
	s_setprio 0
	s_add_i32 s0, s0, s31
	v_lshl_add_u64 v[210:211], v[210:211], 0, s[84:85]
	s_mov_b32 m0, s0
	ds_read_b128 v[162:165], v238 offset:49152
	ds_read_b128 v[166:169], v238 offset:50176
	ds_read_b128 v[170:173], v238 offset:51200
	ds_read_b128 v[174:177], v238 offset:52224
	ds_read_b128 v[178:181], v238 offset:53248
	ds_read_b128 v[182:185], v238 offset:54272
	ds_read_b128 v[202:205], v238 offset:55296
	ds_read_b128 v[206:209], v238 offset:56320
	global_load_lds_dwordx4 v[210:211], off
	s_add_i32 m0, s0, 0x2000
	s_add_u32 s20, s24, 0x160080
	v_lshl_add_u64 v[210:211], v[212:213], 0, s[84:85]
	s_addc_u32 s21, s25, 0
	s_add_i32 s0, s1, s31
	global_load_lds_dwordx4 v[210:211], off
	v_lshl_add_u64 v[210:211], s[20:21], 0, v[186:187]
	s_mov_b32 m0, s0
	s_nop 0
	global_load_lds_dwordx4 v[210:211], off
	v_lshl_add_u64 v[210:211], s[20:21], 0, v[196:197]
	s_add_i32 m0, s0, 0x2000
	s_nop 0
	global_load_lds_dwordx4 v[210:211], off
	v_lshl_add_u64 v[210:211], v[214:215], 0, s[84:85]
	s_mov_b32 m0, s41
	s_nop 0
	global_load_lds_dwordx4 v[210:211], off
	v_lshl_add_u64 v[210:211], v[216:217], 0, s[84:85]
	s_mov_b32 m0, s42
	s_nop 0
	global_load_lds_dwordx4 v[210:211], off
	s_waitcnt vmcnt(8)
	s_waitcnt lgkmcnt(0)
	s_setprio 1
	s_barrier

	v_mfma_f32_16x16x32_bf16 v[62:65], v[90:93], v[162:165], v[62:65]
	v_mfma_f32_16x16x32_bf16 v[62:65], v[102:105], v[166:169], v[62:65]
	v_mfma_f32_16x16x32_bf16 v[58:61], v[126:129], v[166:169], v[58:61]
	v_mfma_f32_16x16x32_bf16 v[58:61], v[114:117], v[162:165], v[58:61]
	v_mfma_f32_16x16x32_bf16 v[42:45], v[114:117], v[170:173], v[42:45]
	v_mfma_f32_16x16x32_bf16 v[42:45], v[126:129], v[174:177], v[42:45]
	v_mfma_f32_16x16x32_bf16 v[46:49], v[102:105], v[174:177], v[46:49]
	v_mfma_f32_16x16x32_bf16 v[46:49], v[90:93], v[170:173], v[46:49]
	v_mfma_f32_16x16x32_bf16 v[30:33], v[90:93], v[178:181], v[30:33]
	v_mfma_f32_16x16x32_bf16 v[30:33], v[102:105], v[182:185], v[30:33]
	v_mfma_f32_16x16x32_bf16 v[26:29], v[126:129], v[182:185], v[26:29]
	v_mfma_f32_16x16x32_bf16 v[26:29], v[114:117], v[178:181], v[26:29]
	v_mfma_f32_16x16x32_bf16 v[10:13], v[114:117], v[202:205], v[10:13]
	v_mfma_f32_16x16x32_bf16 v[10:13], v[126:129], v[206:209], v[10:13]
	v_mfma_f32_16x16x32_bf16 v[14:17], v[102:105], v[206:209], v[14:17]
	v_mfma_f32_16x16x32_bf16 v[14:17], v[90:93], v[202:205], v[14:17]


	v_mfma_f32_16x16x32_bf16 v[54:57], v[138:141], v[162:165], v[54:57]
	v_mfma_f32_16x16x32_bf16 v[54:57], v[142:145], v[166:169], v[54:57]
	v_mfma_f32_16x16x32_bf16 v[50:53], v[158:161], v[166:169], v[50:53]
	v_mfma_f32_16x16x32_bf16 v[50:53], v[154:157], v[162:165], v[50:53]
	v_mfma_f32_16x16x32_bf16 v[34:37], v[154:157], v[170:173], v[34:37]
	v_mfma_f32_16x16x32_bf16 v[34:37], v[158:161], v[174:177], v[34:37]
	v_mfma_f32_16x16x32_bf16 v[38:41], v[142:145], v[174:177], v[38:41]
	v_mfma_f32_16x16x32_bf16 v[38:41], v[138:141], v[170:173], v[38:41]
	v_mfma_f32_16x16x32_bf16 v[22:25], v[138:141], v[178:181], v[22:25]
	v_mfma_f32_16x16x32_bf16 v[22:25], v[142:145], v[182:185], v[22:25]
	v_mfma_f32_16x16x32_bf16 v[18:21], v[158:161], v[182:185], v[18:21]
	v_mfma_f32_16x16x32_bf16 v[18:21], v[154:157], v[178:181], v[18:21]
	v_mfma_f32_16x16x32_bf16 v[2:5], v[154:157], v[202:205], v[2:5]
	v_mfma_f32_16x16x32_bf16 v[2:5], v[158:161], v[206:209], v[2:5]
	v_mfma_f32_16x16x32_bf16 v[6:9], v[142:145], v[206:209], v[6:9]
	v_mfma_f32_16x16x32_bf16 v[6:9], v[138:141], v[202:205], v[6:9]
	s_barrier
	s_setprio 0
	s_add_i32 s51, s51, 2
	s_add_u32 s49, s49, 0x100
	s_addc_u32 s50, s50, 0
	s_cmpk_gt_u32 s51, 0x55
	s_mov_b64 s[20:21], s[22:23]
	s_cbranch_scc0 .LBB0_243
	s_and_b64 vcc, exec, s[16:17]
	s_cbranch_vccz .LBB0_246
	s_barrier

.LBB0_443:
	s_add_u32 s0, s26, 0xfff80080
	s_addc_u32 s1, s27, -1
	s_add_i32 s56, 0, 0x10000
	s_cmp_eq_u32 s55, 28
	s_cselect_b32 s31, s19, s1
	s_cselect_b32 s30, s51, s0
	v_add_u32_e32 v140, s56, v144
	s_cselect_b32 s29, s17, s54
	s_cselect_b32 s28, s52, s53
	s_add_i32 s0, 0, 0x14000
	ds_read_b128 v[146:149], v140
	ds_read_b128 v[150:153], v140 offset:1024
	ds_read_b128 v[154:157], v140 offset:2048
	ds_read_b128 v[158:161], v140 offset:3072
	v_add_u32_e32 v140, s0, v144
	ds_read_b128 v[162:165], v140
	ds_read_b128 v[166:169], v140 offset:1024
	ds_read_b128 v[170:173], v140 offset:2048
	ds_read_b128 v[174:177], v140 offset:3072
	v_lshl_add_u64 v[140:141], s[26:27], 0, v[136:137]
	s_add_i32 m0, s25, 0xc000
	ds_read_b128 v[178:181], v145
	ds_read_b128 v[182:185], v145 offset:1024
	ds_read_b128 v[192:195], v145 offset:2048
	ds_read_b128 v[196:199], v145 offset:3072
	ds_read_b128 v[200:203], v145 offset:4096
	ds_read_b128 v[204:207], v145 offset:5120
	ds_read_b128 v[208:211], v145 offset:6144
	ds_read_b128 v[212:215], v145 offset:7168
	global_load_lds_dwordx4 v[140:141], off
	v_lshl_add_u64 v[140:141], s[26:27], 0, v[138:139]
	s_add_i32 m0, s25, 0xe000
	s_nop 0
	global_load_lds_dwordx4 v[140:141], off
	s_waitcnt vmcnt(8)
	s_waitcnt lgkmcnt(0)
	s_setprio 1
	s_barrier

	v_mfma_f32_16x16x32_bf16 v[126:129], v[146:149], v[178:181], v[126:129]
	v_mfma_f32_16x16x32_bf16 v[126:129], v[150:153], v[182:185], v[126:129]
	v_mfma_f32_16x16x32_bf16 v[122:125], v[158:161], v[182:185], v[122:125]
	v_mfma_f32_16x16x32_bf16 v[122:125], v[154:157], v[178:181], v[122:125]
	v_mfma_f32_16x16x32_bf16 v[106:109], v[154:157], v[192:195], v[106:109]
	v_mfma_f32_16x16x32_bf16 v[106:109], v[158:161], v[196:199], v[106:109]
	v_mfma_f32_16x16x32_bf16 v[114:117], v[150:153], v[196:199], v[114:117]
	v_mfma_f32_16x16x32_bf16 v[114:117], v[146:149], v[192:195], v[114:117]
	v_mfma_f32_16x16x32_bf16 v[98:101], v[146:149], v[200:203], v[98:101]
	v_mfma_f32_16x16x32_bf16 v[98:101], v[150:153], v[204:207], v[98:101]
	v_mfma_f32_16x16x32_bf16 v[90:93], v[158:161], v[204:207], v[90:93]
	v_mfma_f32_16x16x32_bf16 v[90:93], v[154:157], v[200:203], v[90:93]
	v_mfma_f32_16x16x32_bf16 v[74:77], v[154:157], v[208:211], v[74:77]
	v_mfma_f32_16x16x32_bf16 v[74:77], v[158:161], v[212:215], v[74:77]
	v_mfma_f32_16x16x32_bf16 v[82:85], v[150:153], v[212:215], v[82:85]
	v_mfma_f32_16x16x32_bf16 v[82:85], v[146:149], v[208:211], v[82:85]


	v_mfma_f32_16x16x32_bf16 v[118:121], v[162:165], v[178:181], v[118:121]
	v_mfma_f32_16x16x32_bf16 v[118:121], v[166:169], v[182:185], v[118:121]
	v_mfma_f32_16x16x32_bf16 v[110:113], v[174:177], v[182:185], v[110:113]
	v_mfma_f32_16x16x32_bf16 v[110:113], v[170:173], v[178:181], v[110:113]
	v_mfma_f32_16x16x32_bf16 v[94:97], v[170:173], v[192:195], v[94:97]
	v_mfma_f32_16x16x32_bf16 v[94:97], v[174:177], v[196:199], v[94:97]
	v_mfma_f32_16x16x32_bf16 v[102:105], v[166:169], v[196:199], v[102:105]
	v_mfma_f32_16x16x32_bf16 v[102:105], v[162:165], v[192:195], v[102:105]
	v_mfma_f32_16x16x32_bf16 v[86:89], v[162:165], v[200:203], v[86:89]
	v_mfma_f32_16x16x32_bf16 v[86:89], v[166:169], v[204:207], v[86:89]
	v_mfma_f32_16x16x32_bf16 v[78:81], v[174:177], v[204:207], v[78:81]
	v_mfma_f32_16x16x32_bf16 v[78:81], v[170:173], v[200:203], v[78:81]
	v_mfma_f32_16x16x32_bf16 v[66:69], v[170:173], v[208:211], v[66:69]
	v_mfma_f32_16x16x32_bf16 v[66:69], v[174:177], v[212:215], v[66:69]
	v_mfma_f32_16x16x32_bf16 v[70:73], v[166:169], v[212:215], v[70:73]
	v_mfma_f32_16x16x32_bf16 v[70:73], v[162:165], v[208:211], v[70:73]
	s_barrier
	s_setprio 0
	s_add_i32 s1, s56, s39
	v_lshl_add_u64 v[140:141], s[28:29], 0, v[186:187]
	s_mov_b32 m0, s1
	ds_read_b128 v[178:181], v145 offset:16384
	ds_read_b128 v[182:185], v145 offset:17408
	ds_read_b128 v[192:195], v145 offset:18432
	ds_read_b128 v[196:199], v145 offset:19456
	ds_read_b128 v[200:203], v145 offset:20480
	ds_read_b128 v[204:207], v145 offset:21504
	ds_read_b128 v[208:211], v145 offset:22528
	ds_read_b128 v[212:215], v145 offset:23552
	global_load_lds_dwordx4 v[140:141], off
	s_add_i32 m0, s1, 0x2000
	s_add_u32 s56, s28, 0x80000
	v_lshl_add_u64 v[188:189], s[28:29], 0, v[130:131]
	s_addc_u32 s57, s29, 0
	s_add_i32 s0, s0, s39
	global_load_lds_dwordx4 v[188:189], off
	v_lshl_add_u64 v[216:217], s[56:57], 0, v[186:187]
	s_mov_b32 m0, s0
	v_lshl_add_u64 v[218:219], s[30:31], 0, v[132:133]
	global_load_lds_dwordx4 v[216:217], off
	v_lshl_add_u64 v[216:217], s[56:57], 0, v[130:131]
	s_add_i32 m0, s0, 0x2000
	s_nop 0
	global_load_lds_dwordx4 v[216:217], off
	v_lshl_add_u64 v[216:217], s[30:31], 0, v[134:135]
	s_mov_b32 m0, s25
	s_nop 0
	global_load_lds_dwordx4 v[216:217], off
	s_mov_b32 m0, s40
	s_nop 0
	global_load_lds_dwordx4 v[218:219], off
	s_waitcnt vmcnt(8)
	s_waitcnt lgkmcnt(0)
	s_setprio 1
	s_barrier

	v_mfma_f32_16x16x32_bf16 v[62:65], v[146:149], v[178:181], v[62:65]
	v_mfma_f32_16x16x32_bf16 v[62:65], v[150:153], v[182:185], v[62:65]
	v_mfma_f32_16x16x32_bf16 v[58:61], v[158:161], v[182:185], v[58:61]
	v_mfma_f32_16x16x32_bf16 v[58:61], v[154:157], v[178:181], v[58:61]
	v_mfma_f32_16x16x32_bf16 v[42:45], v[154:157], v[192:195], v[42:45]
	v_mfma_f32_16x16x32_bf16 v[42:45], v[158:161], v[196:199], v[42:45]
	v_mfma_f32_16x16x32_bf16 v[50:53], v[150:153], v[196:199], v[50:53]
	v_mfma_f32_16x16x32_bf16 v[50:53], v[146:149], v[192:195], v[50:53]
	v_mfma_f32_16x16x32_bf16 v[34:37], v[146:149], v[200:203], v[34:37]
	v_mfma_f32_16x16x32_bf16 v[34:37], v[150:153], v[204:207], v[34:37]
	v_mfma_f32_16x16x32_bf16 v[26:29], v[158:161], v[204:207], v[26:29]
	v_mfma_f32_16x16x32_bf16 v[26:29], v[154:157], v[200:203], v[26:29]
	v_mfma_f32_16x16x32_bf16 v[10:13], v[154:157], v[208:211], v[10:13]
	v_mfma_f32_16x16x32_bf16 v[10:13], v[158:161], v[212:215], v[10:13]
	v_mfma_f32_16x16x32_bf16 v[18:21], v[150:153], v[212:215], v[18:21]
	v_mfma_f32_16x16x32_bf16 v[18:21], v[146:149], v[208:211], v[18:21]


	v_mfma_f32_16x16x32_bf16 v[54:57], v[162:165], v[178:181], v[54:57]
	v_mfma_f32_16x16x32_bf16 v[54:57], v[166:169], v[182:185], v[54:57]
	v_mfma_f32_16x16x32_bf16 v[46:49], v[174:177], v[182:185], v[46:49]
	v_mfma_f32_16x16x32_bf16 v[46:49], v[170:173], v[178:181], v[46:49]
	v_mfma_f32_16x16x32_bf16 v[30:33], v[170:173], v[192:195], v[30:33]
	v_mfma_f32_16x16x32_bf16 v[30:33], v[174:177], v[196:199], v[30:33]
	v_mfma_f32_16x16x32_bf16 v[38:41], v[166:169], v[196:199], v[38:41]
	v_mfma_f32_16x16x32_bf16 v[38:41], v[162:165], v[192:195], v[38:41]
	v_mfma_f32_16x16x32_bf16 v[22:25], v[162:165], v[200:203], v[22:25]
	v_mfma_f32_16x16x32_bf16 v[22:25], v[166:169], v[204:207], v[22:25]
	v_mfma_f32_16x16x32_bf16 v[14:17], v[174:177], v[204:207], v[14:17]
	v_mfma_f32_16x16x32_bf16 v[14:17], v[170:173], v[200:203], v[14:17]
	v_mfma_f32_16x16x32_bf16 v[2:5], v[170:173], v[208:211], v[2:5]
	v_mfma_f32_16x16x32_bf16 v[2:5], v[174:177], v[212:215], v[2:5]
	v_mfma_f32_16x16x32_bf16 v[6:9], v[166:169], v[212:215], v[6:9]
	v_mfma_f32_16x16x32_bf16 v[6:9], v[162:165], v[208:211], v[6:9]
	s_barrier
	s_setprio 0
	s_add_i32 s0, 0, 0x18000
	s_add_i32 s1, 0, 0x1c000
	v_add_u32_e32 v158, s0, v144
	v_add_u32_e32 v174, s1, v144
	ds_read_b128 v[146:149], v158
	ds_read_b128 v[150:153], v158 offset:1024
	ds_read_b128 v[154:157], v158 offset:2048
	ds_read_b128 v[158:161], v158 offset:3072
	ds_read_b128 v[162:165], v174
	ds_read_b128 v[166:169], v174 offset:1024
	ds_read_b128 v[170:173], v174 offset:2048
	ds_read_b128 v[174:177], v174 offset:3072
	s_add_u32 s30, s30, 0x80000
	s_addc_u32 s31, s31, 0
	s_mov_b32 m0, s41
	v_lshl_add_u64 v[220:221], s[30:31], 0, v[134:135]
	ds_read_b128 v[178:181], v145 offset:32768
	ds_read_b128 v[182:185], v145 offset:33792
	ds_read_b128 v[192:195], v145 offset:34816
	ds_read_b128 v[196:199], v145 offset:35840
	ds_read_b128 v[200:203], v145 offset:36864
	ds_read_b128 v[204:207], v145 offset:37888
	ds_read_b128 v[208:211], v145 offset:38912
	ds_read_b128 v[212:215], v145 offset:39936
	global_load_lds_dwordx4 v[220:221], off
	v_lshl_add_u64 v[220:221], s[30:31], 0, v[132:133]
	s_mov_b32 m0, s42
	s_nop 0
	global_load_lds_dwordx4 v[220:221], off
	s_waitcnt vmcnt(8)
	s_waitcnt lgkmcnt(0)
	s_setprio 1
	s_barrier

	v_mfma_f32_16x16x32_bf16 v[126:129], v[146:149], v[178:181], v[126:129]
	v_mfma_f32_16x16x32_bf16 v[126:129], v[150:153], v[182:185], v[126:129]
	v_mfma_f32_16x16x32_bf16 v[122:125], v[158:161], v[182:185], v[122:125]
	v_mfma_f32_16x16x32_bf16 v[122:125], v[154:157], v[178:181], v[122:125]
	v_mfma_f32_16x16x32_bf16 v[106:109], v[154:157], v[192:195], v[106:109]
	v_mfma_f32_16x16x32_bf16 v[106:109], v[158:161], v[196:199], v[106:109]
	v_mfma_f32_16x16x32_bf16 v[114:117], v[150:153], v[196:199], v[114:117]
	v_mfma_f32_16x16x32_bf16 v[114:117], v[146:149], v[192:195], v[114:117]
	v_mfma_f32_16x16x32_bf16 v[98:101], v[146:149], v[200:203], v[98:101]
	v_mfma_f32_16x16x32_bf16 v[98:101], v[150:153], v[204:207], v[98:101]
	v_mfma_f32_16x16x32_bf16 v[90:93], v[158:161], v[204:207], v[90:93]
	v_mfma_f32_16x16x32_bf16 v[90:93], v[154:157], v[200:203], v[90:93]
	v_mfma_f32_16x16x32_bf16 v[74:77], v[154:157], v[208:211], v[74:77]
	v_mfma_f32_16x16x32_bf16 v[74:77], v[158:161], v[212:215], v[74:77]
	v_mfma_f32_16x16x32_bf16 v[82:85], v[150:153], v[212:215], v[82:85]
	v_mfma_f32_16x16x32_bf16 v[82:85], v[146:149], v[208:211], v[82:85]


	v_mfma_f32_16x16x32_bf16 v[118:121], v[162:165], v[178:181], v[118:121]
	v_mfma_f32_16x16x32_bf16 v[118:121], v[166:169], v[182:185], v[118:121]
	v_mfma_f32_16x16x32_bf16 v[110:113], v[174:177], v[182:185], v[110:113]
	v_mfma_f32_16x16x32_bf16 v[110:113], v[170:173], v[178:181], v[110:113]
	v_mfma_f32_16x16x32_bf16 v[94:97], v[170:173], v[192:195], v[94:97]
	v_mfma_f32_16x16x32_bf16 v[94:97], v[174:177], v[196:199], v[94:97]
	v_mfma_f32_16x16x32_bf16 v[102:105], v[166:169], v[196:199], v[102:105]
	v_mfma_f32_16x16x32_bf16 v[102:105], v[162:165], v[192:195], v[102:105]
	v_mfma_f32_16x16x32_bf16 v[86:89], v[162:165], v[200:203], v[86:89]
	v_mfma_f32_16x16x32_bf16 v[86:89], v[166:169], v[204:207], v[86:89]
	v_mfma_f32_16x16x32_bf16 v[78:81], v[174:177], v[204:207], v[78:81]
	v_mfma_f32_16x16x32_bf16 v[78:81], v[170:173], v[200:203], v[78:81]
	v_mfma_f32_16x16x32_bf16 v[66:69], v[170:173], v[208:211], v[66:69]
	v_mfma_f32_16x16x32_bf16 v[66:69], v[174:177], v[212:215], v[66:69]
	v_mfma_f32_16x16x32_bf16 v[70:73], v[166:169], v[212:215], v[70:73]
	v_mfma_f32_16x16x32_bf16 v[70:73], v[162:165], v[208:211], v[70:73]
	s_barrier
	s_setprio 0
	s_add_i32 s0, s0, s39
	v_lshl_add_u64 v[140:141], v[140:141], 0, s[84:85]
	s_mov_b32 m0, s0
	ds_read_b128 v[178:181], v145 offset:49152
	ds_read_b128 v[182:185], v145 offset:50176
	ds_read_b128 v[192:195], v145 offset:51200
	ds_read_b128 v[196:199], v145 offset:52224
	ds_read_b128 v[200:203], v145 offset:53248
	ds_read_b128 v[204:207], v145 offset:54272
	ds_read_b128 v[208:211], v145 offset:55296
	ds_read_b128 v[212:215], v145 offset:56320
	global_load_lds_dwordx4 v[140:141], off
	s_add_i32 m0, s0, 0x2000
	s_add_u32 s28, s28, 0x80080
	v_lshl_add_u64 v[140:141], v[188:189], 0, s[84:85]
	s_addc_u32 s29, s29, 0
	s_add_i32 s0, s1, s39
	global_load_lds_dwordx4 v[140:141], off
	v_lshl_add_u64 v[140:141], s[28:29], 0, v[186:187]
	s_mov_b32 m0, s0
	s_nop 0
	global_load_lds_dwordx4 v[140:141], off
	v_lshl_add_u64 v[140:141], s[28:29], 0, v[130:131]
	s_add_i32 m0, s0, 0x2000
	s_nop 0
	global_load_lds_dwordx4 v[140:141], off
	v_lshl_add_u64 v[140:141], v[216:217], 0, s[84:85]
	s_mov_b32 m0, s43
	s_nop 0
	global_load_lds_dwordx4 v[140:141], off
	v_lshl_add_u64 v[140:141], v[218:219], 0, s[84:85]
	s_mov_b32 m0, s44
	s_nop 0
	global_load_lds_dwordx4 v[140:141], off
	s_waitcnt vmcnt(8)
	s_waitcnt lgkmcnt(0)
	s_setprio 1
	s_barrier

	v_mfma_f32_16x16x32_bf16 v[62:65], v[146:149], v[178:181], v[62:65]
	v_mfma_f32_16x16x32_bf16 v[62:65], v[150:153], v[182:185], v[62:65]
	v_mfma_f32_16x16x32_bf16 v[58:61], v[158:161], v[182:185], v[58:61]
	v_mfma_f32_16x16x32_bf16 v[58:61], v[154:157], v[178:181], v[58:61]
	v_mfma_f32_16x16x32_bf16 v[42:45], v[154:157], v[192:195], v[42:45]
	v_mfma_f32_16x16x32_bf16 v[42:45], v[158:161], v[196:199], v[42:45]
	v_mfma_f32_16x16x32_bf16 v[50:53], v[150:153], v[196:199], v[50:53]
	v_mfma_f32_16x16x32_bf16 v[50:53], v[146:149], v[192:195], v[50:53]
	v_mfma_f32_16x16x32_bf16 v[34:37], v[146:149], v[200:203], v[34:37]
	v_mfma_f32_16x16x32_bf16 v[34:37], v[150:153], v[204:207], v[34:37]
	v_mfma_f32_16x16x32_bf16 v[26:29], v[158:161], v[204:207], v[26:29]
	v_mfma_f32_16x16x32_bf16 v[26:29], v[154:157], v[200:203], v[26:29]
	v_mfma_f32_16x16x32_bf16 v[10:13], v[154:157], v[208:211], v[10:13]
	v_mfma_f32_16x16x32_bf16 v[10:13], v[158:161], v[212:215], v[10:13]
	v_mfma_f32_16x16x32_bf16 v[18:21], v[150:153], v[212:215], v[18:21]
	v_mfma_f32_16x16x32_bf16 v[18:21], v[146:149], v[208:211], v[18:21]


	v_mfma_f32_16x16x32_bf16 v[54:57], v[162:165], v[178:181], v[54:57]
	v_mfma_f32_16x16x32_bf16 v[54:57], v[166:169], v[182:185], v[54:57]
	v_mfma_f32_16x16x32_bf16 v[46:49], v[174:177], v[182:185], v[46:49]
	v_mfma_f32_16x16x32_bf16 v[46:49], v[170:173], v[178:181], v[46:49]
	v_mfma_f32_16x16x32_bf16 v[30:33], v[170:173], v[192:195], v[30:33]
	v_mfma_f32_16x16x32_bf16 v[30:33], v[174:177], v[196:199], v[30:33]
	v_mfma_f32_16x16x32_bf16 v[38:41], v[166:169], v[196:199], v[38:41]
	v_mfma_f32_16x16x32_bf16 v[38:41], v[162:165], v[192:195], v[38:41]
	v_mfma_f32_16x16x32_bf16 v[22:25], v[162:165], v[200:203], v[22:25]
	v_mfma_f32_16x16x32_bf16 v[22:25], v[166:169], v[204:207], v[22:25]
	v_mfma_f32_16x16x32_bf16 v[14:17], v[174:177], v[204:207], v[14:17]
	v_mfma_f32_16x16x32_bf16 v[14:17], v[170:173], v[200:203], v[14:17]
	v_mfma_f32_16x16x32_bf16 v[2:5], v[170:173], v[208:211], v[2:5]
	v_mfma_f32_16x16x32_bf16 v[2:5], v[174:177], v[212:215], v[2:5]
	v_mfma_f32_16x16x32_bf16 v[6:9], v[166:169], v[212:215], v[6:9]
	v_mfma_f32_16x16x32_bf16 v[6:9], v[162:165], v[208:211], v[6:9]
	s_barrier
	s_setprio 0
	s_add_i32 s55, s55, 2
	s_add_u32 s26, s26, 0x100
	s_addc_u32 s27, s27, 0
	s_add_u32 s53, s53, 0x100
	s_addc_u32 s54, s54, 0
	s_cmp_gt_u32 s55, 29
	s_cbranch_scc0 .LBB0_443
	s_and_b64 vcc, exec, s[14:15]
	s_cbranch_vccz .LBB0_446
	s_barrier

.LBB0_1126:
	s_add_u32 s0, s28, 0xfff80080
	s_addc_u32 s1, s29, -1
	s_add_i32 s54, 0, 0x10000
	s_cmp_eq_u32 s53, 28
	s_cselect_b32 s35, s19, s1
	s_cselect_b32 s34, s25, s0
	s_cselect_b32 s31, s17, s52
	s_cselect_b32 s30, s27, s51
	s_add_i32 s55, 0, 0x14000
	v_add_u32_e32 v126, s54, v237
	v_add_u32_e32 v158, s55, v237
	ds_read_b128 v[90:93], v126
	ds_read_b128 v[102:105], v126 offset:1024
	ds_read_b128 v[114:117], v126 offset:2048
	ds_read_b128 v[126:129], v126 offset:3072
	ds_read_b128 v[138:141], v158
	ds_read_b128 v[142:145], v158 offset:1024
	ds_read_b128 v[154:157], v158 offset:2048
	ds_read_b128 v[158:161], v158 offset:3072
	v_lshl_add_u64 v[188:189], s[28:29], 0, v[198:199]
	s_add_i32 m0, s40, 0xc000
	ds_read_b128 v[162:165], v238
	ds_read_b128 v[166:169], v238 offset:1024
	ds_read_b128 v[170:173], v238 offset:2048
	ds_read_b128 v[174:177], v238 offset:3072
	ds_read_b128 v[178:181], v238 offset:4096
	ds_read_b128 v[182:185], v238 offset:5120
	ds_read_b128 v[202:205], v238 offset:6144
	ds_read_b128 v[206:209], v238 offset:7168
	global_load_lds_dwordx4 v[188:189], off
	v_lshl_add_u64 v[188:189], s[28:29], 0, v[200:201]
	s_add_i32 m0, s40, 0xe000
	s_nop 0
	global_load_lds_dwordx4 v[188:189], off
	s_waitcnt vmcnt(8)
	s_waitcnt lgkmcnt(0)
	s_setprio 1
	s_barrier

	v_mfma_f32_16x16x32_bf16 v[150:153], v[90:93], v[162:165], v[150:153]
	v_mfma_f32_16x16x32_bf16 v[150:153], v[102:105], v[166:169], v[150:153]
	v_mfma_f32_16x16x32_bf16 v[146:149], v[126:129], v[166:169], v[146:149]
	v_mfma_f32_16x16x32_bf16 v[146:149], v[114:117], v[162:165], v[146:149]
	v_mfma_f32_16x16x32_bf16 v[118:121], v[114:117], v[170:173], v[118:121]
	v_mfma_f32_16x16x32_bf16 v[118:121], v[126:129], v[174:177], v[118:121]
	v_mfma_f32_16x16x32_bf16 v[122:125], v[102:105], v[174:177], v[122:125]
	v_mfma_f32_16x16x32_bf16 v[122:125], v[90:93], v[170:173], v[122:125]
	v_mfma_f32_16x16x32_bf16 v[98:101], v[90:93], v[178:181], v[98:101]
	v_mfma_f32_16x16x32_bf16 v[98:101], v[102:105], v[182:185], v[98:101]
	v_mfma_f32_16x16x32_bf16 v[94:97], v[126:129], v[182:185], v[94:97]
	v_mfma_f32_16x16x32_bf16 v[94:97], v[114:117], v[178:181], v[94:97]
	v_mfma_f32_16x16x32_bf16 v[74:77], v[114:117], v[202:205], v[74:77]
	v_mfma_f32_16x16x32_bf16 v[74:77], v[126:129], v[206:209], v[74:77]
	v_mfma_f32_16x16x32_bf16 v[78:81], v[102:105], v[206:209], v[78:81]
	v_mfma_f32_16x16x32_bf16 v[78:81], v[90:93], v[202:205], v[78:81]


	v_mfma_f32_16x16x32_bf16 v[134:137], v[138:141], v[162:165], v[134:137]
	v_mfma_f32_16x16x32_bf16 v[134:137], v[142:145], v[166:169], v[134:137]
	v_mfma_f32_16x16x32_bf16 v[130:133], v[158:161], v[166:169], v[130:133]
	v_mfma_f32_16x16x32_bf16 v[130:133], v[154:157], v[162:165], v[130:133]
	v_mfma_f32_16x16x32_bf16 v[106:109], v[154:157], v[170:173], v[106:109]
	v_mfma_f32_16x16x32_bf16 v[106:109], v[158:161], v[174:177], v[106:109]
	v_mfma_f32_16x16x32_bf16 v[110:113], v[142:145], v[174:177], v[110:113]
	v_mfma_f32_16x16x32_bf16 v[110:113], v[138:141], v[170:173], v[110:113]
	v_mfma_f32_16x16x32_bf16 v[86:89], v[138:141], v[178:181], v[86:89]
	v_mfma_f32_16x16x32_bf16 v[86:89], v[142:145], v[182:185], v[86:89]
	v_mfma_f32_16x16x32_bf16 v[82:85], v[158:161], v[182:185], v[82:85]
	v_mfma_f32_16x16x32_bf16 v[82:85], v[154:157], v[178:181], v[82:85]
	v_mfma_f32_16x16x32_bf16 v[66:69], v[154:157], v[202:205], v[66:69]
	v_mfma_f32_16x16x32_bf16 v[66:69], v[158:161], v[206:209], v[66:69]
	v_mfma_f32_16x16x32_bf16 v[70:73], v[142:145], v[206:209], v[70:73]
	v_mfma_f32_16x16x32_bf16 v[70:73], v[138:141], v[202:205], v[70:73]
	s_barrier
	s_setprio 0
	s_add_i32 s0, s54, s39
	v_lshl_add_u64 v[188:189], s[30:31], 0, v[186:187]
	s_mov_b32 m0, s0
	ds_read_b128 v[162:165], v238 offset:16384
	ds_read_b128 v[166:169], v238 offset:17408
	ds_read_b128 v[170:173], v238 offset:18432
	ds_read_b128 v[174:177], v238 offset:19456
	ds_read_b128 v[178:181], v238 offset:20480
	ds_read_b128 v[182:185], v238 offset:21504
	ds_read_b128 v[202:205], v238 offset:22528
	ds_read_b128 v[206:209], v238 offset:23552
	global_load_lds_dwordx4 v[188:189], off
	s_add_i32 m0, s0, 0x2000
	s_add_u32 s0, s30, 0x80000
	v_lshl_add_u64 v[210:211], s[30:31], 0, v[196:197]
	s_addc_u32 s1, s31, 0
	s_add_i32 s54, s55, s39
	global_load_lds_dwordx4 v[210:211], off
	v_lshl_add_u64 v[212:213], s[0:1], 0, v[186:187]
	s_mov_b32 m0, s54
	v_lshl_add_u64 v[214:215], s[34:35], 0, v[194:195]
	global_load_lds_dwordx4 v[212:213], off
	v_lshl_add_u64 v[212:213], s[0:1], 0, v[196:197]
	s_add_i32 m0, s54, 0x2000
	s_nop 0
	global_load_lds_dwordx4 v[212:213], off
	v_lshl_add_u64 v[212:213], s[34:35], 0, v[192:193]
	s_mov_b32 m0, s40
	s_nop 0
	global_load_lds_dwordx4 v[212:213], off
	s_mov_b32 m0, s41
	s_nop 0
	global_load_lds_dwordx4 v[214:215], off
	s_waitcnt vmcnt(8)
	s_waitcnt lgkmcnt(0)
	s_setprio 1
	s_barrier

	v_mfma_f32_16x16x32_bf16 v[62:65], v[90:93], v[162:165], v[62:65]
	v_mfma_f32_16x16x32_bf16 v[62:65], v[102:105], v[166:169], v[62:65]
	v_mfma_f32_16x16x32_bf16 v[58:61], v[126:129], v[166:169], v[58:61]
	v_mfma_f32_16x16x32_bf16 v[58:61], v[114:117], v[162:165], v[58:61]
	v_mfma_f32_16x16x32_bf16 v[42:45], v[114:117], v[170:173], v[42:45]
	v_mfma_f32_16x16x32_bf16 v[42:45], v[126:129], v[174:177], v[42:45]
	v_mfma_f32_16x16x32_bf16 v[46:49], v[102:105], v[174:177], v[46:49]
	v_mfma_f32_16x16x32_bf16 v[46:49], v[90:93], v[170:173], v[46:49]
	v_mfma_f32_16x16x32_bf16 v[30:33], v[90:93], v[178:181], v[30:33]
	v_mfma_f32_16x16x32_bf16 v[30:33], v[102:105], v[182:185], v[30:33]
	v_mfma_f32_16x16x32_bf16 v[26:29], v[126:129], v[182:185], v[26:29]
	v_mfma_f32_16x16x32_bf16 v[26:29], v[114:117], v[178:181], v[26:29]
	v_mfma_f32_16x16x32_bf16 v[10:13], v[114:117], v[202:205], v[10:13]
	v_mfma_f32_16x16x32_bf16 v[10:13], v[126:129], v[206:209], v[10:13]
	v_mfma_f32_16x16x32_bf16 v[14:17], v[102:105], v[206:209], v[14:17]
	v_mfma_f32_16x16x32_bf16 v[14:17], v[90:93], v[202:205], v[14:17]


	v_mfma_f32_16x16x32_bf16 v[54:57], v[138:141], v[162:165], v[54:57]
	v_mfma_f32_16x16x32_bf16 v[54:57], v[142:145], v[166:169], v[54:57]
	v_mfma_f32_16x16x32_bf16 v[50:53], v[158:161], v[166:169], v[50:53]
	v_mfma_f32_16x16x32_bf16 v[50:53], v[154:157], v[162:165], v[50:53]
	v_mfma_f32_16x16x32_bf16 v[34:37], v[154:157], v[170:173], v[34:37]
	v_mfma_f32_16x16x32_bf16 v[34:37], v[158:161], v[174:177], v[34:37]
	v_mfma_f32_16x16x32_bf16 v[38:41], v[142:145], v[174:177], v[38:41]
	v_mfma_f32_16x16x32_bf16 v[38:41], v[138:141], v[170:173], v[38:41]
	v_mfma_f32_16x16x32_bf16 v[22:25], v[138:141], v[178:181], v[22:25]
	v_mfma_f32_16x16x32_bf16 v[22:25], v[142:145], v[182:185], v[22:25]
	v_mfma_f32_16x16x32_bf16 v[18:21], v[158:161], v[182:185], v[18:21]
	v_mfma_f32_16x16x32_bf16 v[18:21], v[154:157], v[178:181], v[18:21]
	v_mfma_f32_16x16x32_bf16 v[2:5], v[154:157], v[202:205], v[2:5]
	v_mfma_f32_16x16x32_bf16 v[2:5], v[158:161], v[206:209], v[2:5]
	v_mfma_f32_16x16x32_bf16 v[6:9], v[142:145], v[206:209], v[6:9]
	v_mfma_f32_16x16x32_bf16 v[6:9], v[138:141], v[202:205], v[6:9]
	s_barrier
	s_setprio 0
	s_add_i32 s54, 0, 0x18000
	s_add_i32 s55, 0, 0x1c000
	v_add_u32_e32 v126, s54, v237
	v_add_u32_e32 v158, s55, v237
	ds_read_b128 v[90:93], v126
	ds_read_b128 v[102:105], v126 offset:1024
	ds_read_b128 v[114:117], v126 offset:2048
	ds_read_b128 v[126:129], v126 offset:3072
	ds_read_b128 v[138:141], v158
	ds_read_b128 v[142:145], v158 offset:1024
	ds_read_b128 v[154:157], v158 offset:2048
	ds_read_b128 v[158:161], v158 offset:3072
	s_add_u32 s0, s34, 0x80000
	s_addc_u32 s1, s35, 0
	s_mov_b32 m0, s42
	v_lshl_add_u64 v[216:217], s[0:1], 0, v[192:193]
	ds_read_b128 v[162:165], v238 offset:32768
	ds_read_b128 v[166:169], v238 offset:33792
	ds_read_b128 v[170:173], v238 offset:34816
	ds_read_b128 v[174:177], v238 offset:35840
	ds_read_b128 v[178:181], v238 offset:36864
	ds_read_b128 v[182:185], v238 offset:37888
	ds_read_b128 v[202:205], v238 offset:38912
	ds_read_b128 v[206:209], v238 offset:39936
	global_load_lds_dwordx4 v[216:217], off
	v_lshl_add_u64 v[216:217], s[0:1], 0, v[194:195]
	s_mov_b32 m0, s43
	s_nop 0
	global_load_lds_dwordx4 v[216:217], off
	s_waitcnt vmcnt(8)
	s_waitcnt lgkmcnt(0)
	s_setprio 1
	s_barrier

	v_mfma_f32_16x16x32_bf16 v[150:153], v[90:93], v[162:165], v[150:153]
	v_mfma_f32_16x16x32_bf16 v[150:153], v[102:105], v[166:169], v[150:153]
	v_mfma_f32_16x16x32_bf16 v[146:149], v[126:129], v[166:169], v[146:149]
	v_mfma_f32_16x16x32_bf16 v[146:149], v[114:117], v[162:165], v[146:149]
	v_mfma_f32_16x16x32_bf16 v[118:121], v[114:117], v[170:173], v[118:121]
	v_mfma_f32_16x16x32_bf16 v[118:121], v[126:129], v[174:177], v[118:121]
	v_mfma_f32_16x16x32_bf16 v[122:125], v[102:105], v[174:177], v[122:125]
	v_mfma_f32_16x16x32_bf16 v[122:125], v[90:93], v[170:173], v[122:125]
	v_mfma_f32_16x16x32_bf16 v[98:101], v[90:93], v[178:181], v[98:101]
	v_mfma_f32_16x16x32_bf16 v[98:101], v[102:105], v[182:185], v[98:101]
	v_mfma_f32_16x16x32_bf16 v[94:97], v[126:129], v[182:185], v[94:97]
	v_mfma_f32_16x16x32_bf16 v[94:97], v[114:117], v[178:181], v[94:97]
	v_mfma_f32_16x16x32_bf16 v[74:77], v[114:117], v[202:205], v[74:77]
	v_mfma_f32_16x16x32_bf16 v[74:77], v[126:129], v[206:209], v[74:77]
	v_mfma_f32_16x16x32_bf16 v[78:81], v[102:105], v[206:209], v[78:81]
	v_mfma_f32_16x16x32_bf16 v[78:81], v[90:93], v[202:205], v[78:81]


	v_mfma_f32_16x16x32_bf16 v[134:137], v[138:141], v[162:165], v[134:137]
	v_mfma_f32_16x16x32_bf16 v[134:137], v[142:145], v[166:169], v[134:137]
	v_mfma_f32_16x16x32_bf16 v[130:133], v[158:161], v[166:169], v[130:133]
	v_mfma_f32_16x16x32_bf16 v[130:133], v[154:157], v[162:165], v[130:133]
	v_mfma_f32_16x16x32_bf16 v[106:109], v[154:157], v[170:173], v[106:109]
	v_mfma_f32_16x16x32_bf16 v[106:109], v[158:161], v[174:177], v[106:109]
	v_mfma_f32_16x16x32_bf16 v[110:113], v[142:145], v[174:177], v[110:113]
	v_mfma_f32_16x16x32_bf16 v[110:113], v[138:141], v[170:173], v[110:113]
	v_mfma_f32_16x16x32_bf16 v[86:89], v[138:141], v[178:181], v[86:89]
	v_mfma_f32_16x16x32_bf16 v[86:89], v[142:145], v[182:185], v[86:89]
	v_mfma_f32_16x16x32_bf16 v[82:85], v[158:161], v[182:185], v[82:85]
	v_mfma_f32_16x16x32_bf16 v[82:85], v[154:157], v[178:181], v[82:85]
	v_mfma_f32_16x16x32_bf16 v[66:69], v[154:157], v[202:205], v[66:69]
	v_mfma_f32_16x16x32_bf16 v[66:69], v[158:161], v[206:209], v[66:69]
	v_mfma_f32_16x16x32_bf16 v[70:73], v[142:145], v[206:209], v[70:73]
	v_mfma_f32_16x16x32_bf16 v[70:73], v[138:141], v[202:205], v[70:73]
	s_barrier
	s_setprio 0
	s_add_i32 s0, s54, s39
	v_lshl_add_u64 v[188:189], v[188:189], 0, s[84:85]
	s_mov_b32 m0, s0
	ds_read_b128 v[162:165], v238 offset:49152
	ds_read_b128 v[166:169], v238 offset:50176
	ds_read_b128 v[170:173], v238 offset:51200
	ds_read_b128 v[174:177], v238 offset:52224
	ds_read_b128 v[178:181], v238 offset:53248
	ds_read_b128 v[182:185], v238 offset:54272
	ds_read_b128 v[202:205], v238 offset:55296
	ds_read_b128 v[206:209], v238 offset:56320
	global_load_lds_dwordx4 v[188:189], off
	s_add_i32 m0, s0, 0x2000
	s_add_u32 s0, s30, 0x80080
	v_lshl_add_u64 v[188:189], v[210:211], 0, s[84:85]
	s_addc_u32 s1, s31, 0
	s_add_i32 s30, s55, s39
	global_load_lds_dwordx4 v[188:189], off
	v_lshl_add_u64 v[188:189], s[0:1], 0, v[186:187]
	s_mov_b32 m0, s30
	s_nop 0
	global_load_lds_dwordx4 v[188:189], off
	v_lshl_add_u64 v[188:189], s[0:1], 0, v[196:197]
	s_add_i32 m0, s30, 0x2000
	s_nop 0
	global_load_lds_dwordx4 v[188:189], off
	v_lshl_add_u64 v[188:189], v[212:213], 0, s[84:85]
	s_mov_b32 m0, s47
	s_nop 0
	global_load_lds_dwordx4 v[188:189], off
	v_lshl_add_u64 v[188:189], v[214:215], 0, s[84:85]
	s_mov_b32 m0, s48
	s_nop 0
	global_load_lds_dwordx4 v[188:189], off
	s_waitcnt vmcnt(8)
	s_waitcnt lgkmcnt(0)
	s_setprio 1
	s_barrier

	v_mfma_f32_16x16x32_bf16 v[62:65], v[90:93], v[162:165], v[62:65]
	v_mfma_f32_16x16x32_bf16 v[62:65], v[102:105], v[166:169], v[62:65]
	v_mfma_f32_16x16x32_bf16 v[58:61], v[126:129], v[166:169], v[58:61]
	v_mfma_f32_16x16x32_bf16 v[58:61], v[114:117], v[162:165], v[58:61]
	v_mfma_f32_16x16x32_bf16 v[42:45], v[114:117], v[170:173], v[42:45]
	v_mfma_f32_16x16x32_bf16 v[42:45], v[126:129], v[174:177], v[42:45]
	v_mfma_f32_16x16x32_bf16 v[46:49], v[102:105], v[174:177], v[46:49]
	v_mfma_f32_16x16x32_bf16 v[46:49], v[90:93], v[170:173], v[46:49]
	v_mfma_f32_16x16x32_bf16 v[30:33], v[90:93], v[178:181], v[30:33]
	v_mfma_f32_16x16x32_bf16 v[30:33], v[102:105], v[182:185], v[30:33]
	v_mfma_f32_16x16x32_bf16 v[26:29], v[126:129], v[182:185], v[26:29]
	v_mfma_f32_16x16x32_bf16 v[26:29], v[114:117], v[178:181], v[26:29]
	v_mfma_f32_16x16x32_bf16 v[10:13], v[114:117], v[202:205], v[10:13]
	v_mfma_f32_16x16x32_bf16 v[10:13], v[126:129], v[206:209], v[10:13]
	v_mfma_f32_16x16x32_bf16 v[14:17], v[102:105], v[206:209], v[14:17]
	v_mfma_f32_16x16x32_bf16 v[14:17], v[90:93], v[202:205], v[14:17]


	v_mfma_f32_16x16x32_bf16 v[54:57], v[138:141], v[162:165], v[54:57]
	v_mfma_f32_16x16x32_bf16 v[54:57], v[142:145], v[166:169], v[54:57]
	v_mfma_f32_16x16x32_bf16 v[50:53], v[158:161], v[166:169], v[50:53]
	v_mfma_f32_16x16x32_bf16 v[50:53], v[154:157], v[162:165], v[50:53]
	v_mfma_f32_16x16x32_bf16 v[34:37], v[154:157], v[170:173], v[34:37]
	v_mfma_f32_16x16x32_bf16 v[34:37], v[158:161], v[174:177], v[34:37]
	v_mfma_f32_16x16x32_bf16 v[38:41], v[142:145], v[174:177], v[38:41]
	v_mfma_f32_16x16x32_bf16 v[38:41], v[138:141], v[170:173], v[38:41]
	v_mfma_f32_16x16x32_bf16 v[22:25], v[138:141], v[178:181], v[22:25]
	v_mfma_f32_16x16x32_bf16 v[22:25], v[142:145], v[182:185], v[22:25]
	v_mfma_f32_16x16x32_bf16 v[18:21], v[158:161], v[182:185], v[18:21]
	v_mfma_f32_16x16x32_bf16 v[18:21], v[154:157], v[178:181], v[18:21]
	v_mfma_f32_16x16x32_bf16 v[2:5], v[154:157], v[202:205], v[2:5]
	v_mfma_f32_16x16x32_bf16 v[2:5], v[158:161], v[206:209], v[2:5]
	v_mfma_f32_16x16x32_bf16 v[6:9], v[142:145], v[206:209], v[6:9]
	v_mfma_f32_16x16x32_bf16 v[6:9], v[138:141], v[202:205], v[6:9]
	s_barrier
	s_setprio 0
	s_add_i32 s53, s53, 2
	s_add_u32 s28, s28, 0x100
	s_addc_u32 s29, s29, 0
	s_add_u32 s51, s51, 0x100
	s_addc_u32 s52, s52, 0
	s_cmp_gt_u32 s53, 29
	s_cbranch_scc0 .LBB0_1126
	s_and_b64 vcc, exec, s[14:15]
	s_cbranch_vccz .LBB0_1129
	s_barrier
